# GU and residual GEMMs: epilogues un-aligned (leading half no longer waits for trailing last MFMA block except on last unit)
# baseline (speedup 1.0000x reference)
; #define PG8_BAR __builtin_amdgcn_s_barrier()
; template <class Epi, class Sched, bool ALIGN_EPI = false, bool SP2 = false, bool F16 = false>
; __device__ __forceinline__ void gemm_phase(PG8_LAS unsigned char* lds, const Gemm g, const Sched& S, const Epi& E) {
;     ...
;         if constexpr (ALIGN_EPI) { if (wr == 0) PG8_BAR; }
;         if constexpr (!Epi::AFTER_DRAIN) { E(acc, cur, wr, wc, fr, fq); S.done(cur); }
.LBB0_311:
	s_and_b64 vcc, s[36:37], s[40:41]
	s_cbranch_vccz .LBB0_313
	s_barrier

; __device__ __forceinline__ unsigned cvt_pk_bf16(float lo, float hi) { unsigned r; asm volatile("v_cvt_pk_bf16_f32 %0, %1, %2" : "=v"(r) : "v"(lo), "v"(hi)); return r; }
;     __device__ __forceinline__ void operator()(const f32x4 (&acc)[2][2][4][2], const Unit& u, int wr, int wc, int fr, int fq) const {
;     ...
;         for (int ai = 0; ai < 2; ++ai)
; #pragma unroll
;             for (int m = 0; m < 4; ++m) {
;                 const int row = row0 + ai * HALF + m * 16;
;                 const float rs = rsa[ai][m];
;                 float h[8];
; #pragma unroll
;                 for (int n = 0; n < 2; ++n)
; #pragma unroll
;                     for (int e = 0; e < 4; ++e) {
;                         const float g = acc[ai][0][m][n][e] * rs, uu = acc[ai][1][m][n][e] * rs;
;                         const float sg = __builtin_amdgcn_rcpf(1.f + __builtin_amdgcn_exp2f(g * -1.4426950408889634f));
;                         h[n * 4 + e] = g * sg * uu;
;                     }
;                 u32x4 w; w.x = cvt_pk_bf16(h[0], h[1]); w.y = cvt_pk_bf16(h[2], h[3]); w.z = cvt_pk_bf16(h[4], h[5]); w.w = cvt_pk_bf16(h[6], h[7]);
;                 *(u32x4*)(H + (size_t)row * ldc + u.pn * HALF + wc * 32 + 8 * fq) = w;
.LBB0_317:
	v_mov_b32_e32 v132, v126
	v_mov_b32_e32 v133, v122
	v_pk_mul_f32 v[132:133], v[132:133], v[186:187] op_sel_hi:[1,0]
	s_lshl_b32 s52, s78, 7
	v_mul_f32_e32 v122, 0xbfb8aa3b, v133
	v_exp_f32_e32 v122, v122
	s_ashr_i32 s53, s52, 31
	s_lshl_b64 s[52:53], s[52:53], 1
	s_and_b64 vcc, exec, s[36:37]
	v_add_f32_e32 v122, 1.0, v122
	v_rcp_f32_e32 v122, v122
	s_nop 0
	v_mul_f32_e32 v122, v133, v122
	v_mul_f32_e32 v126, v132, v122
	v_mov_b32_e32 v122, v127
	v_pk_mul_f32 v[122:123], v[122:123], v[186:187] op_sel_hi:[1,0]
	s_nop 0
	v_mul_f32_e32 v127, 0xbfb8aa3b, v123
	v_exp_f32_e32 v127, v127
	s_nop 0
	v_add_f32_e32 v127, 1.0, v127
	v_rcp_f32_e32 v127, v127
	s_nop 0
	v_mul_f32_e32 v123, v123, v127
	v_mul_f32_e32 v127, v122, v123
	v_mov_b32_e32 v122, v128
	v_mov_b32_e32 v123, v124
	v_pk_mul_f32 v[122:123], v[122:123], v[186:187] op_sel_hi:[1,0]
	s_nop 0
	v_mul_f32_e32 v124, 0xbfb8aa3b, v123
	v_exp_f32_e32 v124, v124
	s_nop 0
	v_add_f32_e32 v124, 1.0, v124
	v_rcp_f32_e32 v124, v124
	s_nop 0
	v_mul_f32_e32 v123, v123, v124
	v_mov_b32_e32 v124, v129
	v_mul_f32_e32 v128, v122, v123
	v_pk_mul_f32 v[122:123], v[124:125], v[186:187] op_sel_hi:[1,0]
	s_nop 0
	v_mul_f32_e32 v124, 0xbfb8aa3b, v123
	v_exp_f32_e32 v124, v124
	s_nop 0
	v_add_f32_e32 v124, 1.0, v124
	v_rcp_f32_e32 v124, v124
	s_nop 0
	v_mul_f32_e32 v123, v123, v124
	v_mul_f32_e32 v124, v122, v123
	v_mov_b32_e32 v122, v118
	v_mov_b32_e32 v123, v114
	v_pk_mul_f32 v[122:123], v[122:123], v[186:187] op_sel_hi:[1,0]
	s_nop 0
	v_mul_f32_e32 v114, 0xbfb8aa3b, v123
	v_exp_f32_e32 v114, v114
	s_nop 0
	v_add_f32_e32 v114, 1.0, v114
	v_rcp_f32_e32 v114, v114
	s_nop 0
	v_mul_f32_e32 v114, v123, v114
	v_mul_f32_e32 v118, v122, v114
	v_mov_b32_e32 v114, v119
	v_pk_mul_f32 v[114:115], v[114:115], v[186:187] op_sel_hi:[1,0]
	s_nop 0
	v_mul_f32_e32 v119, 0xbfb8aa3b, v115
	v_exp_f32_e32 v119, v119
	s_nop 0
	v_add_f32_e32 v119, 1.0, v119
	v_rcp_f32_e32 v119, v119
	s_nop 0
	v_mul_f32_e32 v115, v115, v119
	v_mul_f32_e32 v119, v114, v115
	v_mov_b32_e32 v114, v120
	v_mov_b32_e32 v115, v116
	v_pk_mul_f32 v[114:115], v[114:115], v[186:187] op_sel_hi:[1,0]
	s_nop 0
	v_mul_f32_e32 v116, 0xbfb8aa3b, v115
	v_exp_f32_e32 v116, v116
	s_nop 0
	v_add_f32_e32 v116, 1.0, v116
	v_rcp_f32_e32 v116, v116
	s_nop 0
	v_mul_f32_e32 v115, v115, v116
	v_mov_b32_e32 v116, v121
	v_mul_f32_e32 v120, v114, v115
	v_pk_mul_f32 v[114:115], v[116:117], v[186:187] op_sel_hi:[1,0]
	s_nop 0
	v_mul_f32_e32 v116, 0xbfb8aa3b, v115
	v_exp_f32_e32 v116, v116
	s_nop 0
	v_add_f32_e32 v116, 1.0, v116
	v_rcp_f32_e32 v116, v116
	s_nop 0
	v_mul_f32_e32 v115, v115, v116
	v_mul_f32_e32 v114, v114, v115
	v_cvt_pk_bf16_f32 v116, v126, v127
	v_cvt_pk_bf16_f32 v117, v128, v124
	v_cvt_pk_bf16_f32 v118, v118, v119
	v_cvt_pk_bf16_f32 v119, v120, v114
	v_mov_b64_e32 v[114:115], s[76:77]
	v_mad_u64_u32 v[120:121], s[54:55], v184, s63, v[114:115]
	v_mov_b32_e32 v122, v121
	v_mad_u64_u32 v[122:123], s[54:55], v185, s63, v[122:123]
	v_mov_b32_e32 v121, v122
	v_lshl_add_u64 v[120:121], v[120:121], 0, s[52:53]
	v_lshl_add_u64 v[120:121], v[120:121], 0, s[24:25]
	v_lshl_add_u64 v[120:121], v[120:121], 0, v[174:175]
	global_store_dwordx4 v[120:121], v[116:119], off
	s_nop 1
	v_mov_b32_e32 v116, v110
	v_mov_b32_e32 v117, v106
	v_pk_mul_f32 v[116:117], v[116:117], v[182:183] op_sel_hi:[1,0]
	s_nop 0
	v_mul_f32_e32 v106, 0xbfb8aa3b, v117
	v_exp_f32_e32 v106, v106
	s_nop 0
	v_add_f32_e32 v106, 1.0, v106
	v_rcp_f32_e32 v106, v106
	s_nop 0
	v_mul_f32_e32 v106, v117, v106
	v_mul_f32_e32 v110, v116, v106
	v_mov_b32_e32 v106, v111
	v_pk_mul_f32 v[106:107], v[106:107], v[182:183] op_sel_hi:[1,0]
	s_nop 0
	v_mul_f32_e32 v111, 0xbfb8aa3b, v107
	v_exp_f32_e32 v111, v111
	s_nop 0
	v_add_f32_e32 v111, 1.0, v111
	v_rcp_f32_e32 v111, v111
	s_nop 0
	v_mul_f32_e32 v107, v107, v111
	v_mul_f32_e32 v111, v106, v107
	v_mov_b32_e32 v106, v112
	v_mov_b32_e32 v107, v108
	v_pk_mul_f32 v[106:107], v[106:107], v[182:183] op_sel_hi:[1,0]
	s_nop 0
	v_mul_f32_e32 v108, 0xbfb8aa3b, v107
	v_exp_f32_e32 v108, v108
	s_nop 0
	v_add_f32_e32 v108, 1.0, v108
	v_rcp_f32_e32 v108, v108
	s_nop 0
	v_mul_f32_e32 v107, v107, v108
	v_mov_b32_e32 v108, v113
	v_mul_f32_e32 v112, v106, v107
	v_pk_mul_f32 v[106:107], v[108:109], v[182:183] op_sel_hi:[1,0]
	s_nop 0
	v_mul_f32_e32 v108, 0xbfb8aa3b, v107
	v_exp_f32_e32 v108, v108
	s_nop 0
	v_add_f32_e32 v108, 1.0, v108
	v_rcp_f32_e32 v108, v108
	s_nop 0
	v_mul_f32_e32 v107, v107, v108
	v_mul_f32_e32 v108, v106, v107
	v_mov_b32_e32 v106, v102
	v_mov_b32_e32 v107, v98
	v_pk_mul_f32 v[106:107], v[106:107], v[182:183] op_sel_hi:[1,0]
	s_nop 0
	v_mul_f32_e32 v98, 0xbfb8aa3b, v107
	v_exp_f32_e32 v98, v98
	s_nop 0
	v_add_f32_e32 v98, 1.0, v98
	v_rcp_f32_e32 v98, v98
	s_nop 0
	v_mul_f32_e32 v98, v107, v98
	v_mul_f32_e32 v102, v106, v98
	v_mov_b32_e32 v98, v103
	v_pk_mul_f32 v[98:99], v[98:99], v[182:183] op_sel_hi:[1,0]
	s_nop 0
	v_mul_f32_e32 v103, 0xbfb8aa3b, v99
	v_exp_f32_e32 v103, v103
	s_nop 0
	v_add_f32_e32 v103, 1.0, v103
	v_rcp_f32_e32 v103, v103
	s_nop 0
	v_mul_f32_e32 v99, v99, v103
	v_mul_f32_e32 v103, v98, v99
	v_mov_b32_e32 v98, v104
	v_mov_b32_e32 v99, v100
	v_pk_mul_f32 v[98:99], v[98:99], v[182:183] op_sel_hi:[1,0]
	s_nop 0
	v_mul_f32_e32 v100, 0xbfb8aa3b, v99
	v_exp_f32_e32 v100, v100
	s_nop 0
	v_add_f32_e32 v100, 1.0, v100
	v_rcp_f32_e32 v100, v100
	s_nop 0
	v_mul_f32_e32 v99, v99, v100
	v_mov_b32_e32 v100, v105
	v_mul_f32_e32 v104, v98, v99
	v_pk_mul_f32 v[98:99], v[100:101], v[182:183] op_sel_hi:[1,0]
	s_nop 0
	v_mul_f32_e32 v100, 0xbfb8aa3b, v99
	v_exp_f32_e32 v100, v100
	s_nop 0
	v_add_f32_e32 v100, 1.0, v100
	v_rcp_f32_e32 v100, v100
	s_nop 0
; __device__ __forceinline__ unsigned cvt_pk_bf16(float lo, float hi) { unsigned r; asm volatile("v_cvt_pk_bf16_f32 %0, %1, %2" : "=v"(r) : "v"(lo), "v"(hi)); return r; }
;     __device__ __forceinline__ void operator()(const f32x4 (&acc)[2][2][4][2], const Unit& u, int wr, int wc, int fr, int fq) const {
;     ...
;         for (int ai = 0; ai < 2; ++ai)
; #pragma unroll
;             for (int m = 0; m < 4; ++m) {
;                 const int row = row0 + ai * HALF + m * 16;
;                 const float rs = rsa[ai][m];
;                 float h[8];
; #pragma unroll
;                 for (int n = 0; n < 2; ++n)
; #pragma unroll
;                     for (int e = 0; e < 4; ++e) {
;                         const float g = acc[ai][0][m][n][e] * rs, uu = acc[ai][1][m][n][e] * rs;
;                         const float sg = __builtin_amdgcn_rcpf(1.f + __builtin_amdgcn_exp2f(g * -1.4426950408889634f));
;                         h[n * 4 + e] = g * sg * uu;
;                     }
;                 u32x4 w; w.x = cvt_pk_bf16(h[0], h[1]); w.y = cvt_pk_bf16(h[2], h[3]); w.z = cvt_pk_bf16(h[4], h[5]); w.w = cvt_pk_bf16(h[6], h[7]);
;                 *(u32x4*)(H + (size_t)row * ldc + u.pn * HALF + wc * 32 + 8 * fq) = w;
	v_mul_f32_e32 v99, v99, v100
	v_mul_f32_e32 v101, v98, v99
	v_cvt_pk_bf16_f32 v98, v110, v111
	v_cvt_pk_bf16_f32 v99, v112, v108
	v_cvt_pk_bf16_f32 v100, v102, v103
	v_mad_u64_u32 v[102:103], s[54:55], v172, s63, v[114:115]
	v_cvt_pk_bf16_f32 v101, v104, v101
	v_mov_b32_e32 v104, v103
	v_mad_u64_u32 v[104:105], s[54:55], v173, s63, v[104:105]
	v_mov_b32_e32 v103, v104
	v_lshl_add_u64 v[102:103], v[102:103], 0, s[52:53]
	v_lshl_add_u64 v[102:103], v[102:103], 0, s[24:25]
	v_lshl_add_u64 v[102:103], v[102:103], 0, v[174:175]
	global_store_dwordx4 v[102:103], v[98:101], off
	s_nop 1
	v_mov_b32_e32 v98, v94
	v_mov_b32_e32 v99, v90
	v_pk_mul_f32 v[98:99], v[98:99], v[176:177] op_sel_hi:[1,0]
	s_nop 0
	v_mul_f32_e32 v90, 0xbfb8aa3b, v99
	v_exp_f32_e32 v90, v90
	s_nop 0
	v_add_f32_e32 v90, 1.0, v90
	v_rcp_f32_e32 v90, v90
	s_nop 0
	v_mul_f32_e32 v90, v99, v90
	v_mul_f32_e32 v94, v98, v90
	v_mov_b32_e32 v90, v95
	v_pk_mul_f32 v[90:91], v[90:91], v[176:177] op_sel_hi:[1,0]
	s_nop 0
	v_mul_f32_e32 v95, 0xbfb8aa3b, v91
	v_exp_f32_e32 v95, v95
	s_nop 0
	v_add_f32_e32 v95, 1.0, v95
	v_rcp_f32_e32 v95, v95
	s_nop 0
	v_mul_f32_e32 v91, v91, v95
	v_mul_f32_e32 v95, v90, v91
	v_mov_b32_e32 v90, v96
	v_mov_b32_e32 v91, v92
	v_pk_mul_f32 v[90:91], v[90:91], v[176:177] op_sel_hi:[1,0]
	s_nop 0
	v_mul_f32_e32 v92, 0xbfb8aa3b, v91
	v_exp_f32_e32 v92, v92
	s_nop 0
	v_add_f32_e32 v92, 1.0, v92
	v_rcp_f32_e32 v92, v92
	s_nop 0
	v_mul_f32_e32 v91, v91, v92
	v_mov_b32_e32 v92, v97
	v_mul_f32_e32 v96, v90, v91
	v_pk_mul_f32 v[90:91], v[92:93], v[176:177] op_sel_hi:[1,0]
	s_nop 0
	v_mul_f32_e32 v92, 0xbfb8aa3b, v91
	v_exp_f32_e32 v92, v92
	s_nop 0
	v_add_f32_e32 v92, 1.0, v92
	v_rcp_f32_e32 v92, v92
	s_nop 0
	v_mul_f32_e32 v91, v91, v92
	v_mul_f32_e32 v92, v90, v91
	v_mov_b32_e32 v90, v86
	v_mov_b32_e32 v91, v82
	v_pk_mul_f32 v[90:91], v[90:91], v[176:177] op_sel_hi:[1,0]
	s_nop 0
	v_mul_f32_e32 v82, 0xbfb8aa3b, v91
	v_exp_f32_e32 v82, v82
	s_nop 0
	v_add_f32_e32 v82, 1.0, v82
	v_rcp_f32_e32 v82, v82
	s_nop 0
	v_mul_f32_e32 v82, v91, v82
	v_mul_f32_e32 v86, v90, v82
	v_mov_b32_e32 v82, v87
	v_pk_mul_f32 v[82:83], v[82:83], v[176:177] op_sel_hi:[1,0]
	s_nop 0
	v_mul_f32_e32 v87, 0xbfb8aa3b, v83
	v_exp_f32_e32 v87, v87
	s_nop 0
	v_add_f32_e32 v87, 1.0, v87
	v_rcp_f32_e32 v87, v87
	s_nop 0
	v_mul_f32_e32 v83, v83, v87
	v_mul_f32_e32 v87, v82, v83
	v_mov_b32_e32 v82, v88
	v_mov_b32_e32 v83, v84
	v_pk_mul_f32 v[82:83], v[82:83], v[176:177] op_sel_hi:[1,0]
	s_nop 0
	v_mul_f32_e32 v84, 0xbfb8aa3b, v83
	v_exp_f32_e32 v84, v84
	s_nop 0
	v_add_f32_e32 v84, 1.0, v84
	v_rcp_f32_e32 v84, v84
	s_nop 0
	v_mul_f32_e32 v83, v83, v84
	v_mov_b32_e32 v84, v89
	v_mul_f32_e32 v88, v82, v83
	v_pk_mul_f32 v[82:83], v[84:85], v[176:177] op_sel_hi:[1,0]
	s_nop 0
	v_mul_f32_e32 v84, 0xbfb8aa3b, v83
	v_exp_f32_e32 v84, v84
	s_nop 0
	v_add_f32_e32 v84, 1.0, v84
	v_rcp_f32_e32 v84, v84
	s_nop 0
	v_mul_f32_e32 v83, v83, v84
	v_mul_f32_e32 v85, v82, v83
	v_cvt_pk_bf16_f32 v82, v94, v95
	v_cvt_pk_bf16_f32 v83, v96, v92
	v_cvt_pk_bf16_f32 v84, v86, v87
	v_mad_u64_u32 v[86:87], s[54:55], v168, s63, v[114:115]
	v_cvt_pk_bf16_f32 v85, v88, v85
	v_mov_b32_e32 v88, v87
	v_mad_u64_u32 v[88:89], s[54:55], v169, s63, v[88:89]
	v_mov_b32_e32 v87, v88
	v_lshl_add_u64 v[86:87], v[86:87], 0, s[52:53]
	v_lshl_add_u64 v[86:87], v[86:87], 0, s[24:25]
	v_lshl_add_u64 v[86:87], v[86:87], 0, v[174:175]
	global_store_dwordx4 v[86:87], v[82:85], off
	s_nop 1
	v_mov_b32_e32 v82, v78
	v_mov_b32_e32 v83, v74
	v_pk_mul_f32 v[82:83], v[82:83], v[170:171] op_sel_hi:[1,0]
	s_nop 0
	v_mul_f32_e32 v74, 0xbfb8aa3b, v83
	v_exp_f32_e32 v74, v74
	s_nop 0
	v_add_f32_e32 v74, 1.0, v74
	v_rcp_f32_e32 v74, v74
	s_nop 0
	v_mul_f32_e32 v74, v83, v74
	v_mul_f32_e32 v78, v82, v74
	v_mov_b32_e32 v74, v79
	v_pk_mul_f32 v[74:75], v[74:75], v[170:171] op_sel_hi:[1,0]
	s_nop 0
	v_mul_f32_e32 v79, 0xbfb8aa3b, v75
	v_exp_f32_e32 v79, v79
	s_nop 0
	v_add_f32_e32 v79, 1.0, v79
	v_rcp_f32_e32 v79, v79
	s_nop 0
	v_mul_f32_e32 v75, v75, v79
	v_mul_f32_e32 v79, v74, v75
	v_mov_b32_e32 v74, v80
	v_mov_b32_e32 v75, v76
	v_pk_mul_f32 v[74:75], v[74:75], v[170:171] op_sel_hi:[1,0]
	s_nop 0
	v_mul_f32_e32 v76, 0xbfb8aa3b, v75
	v_exp_f32_e32 v76, v76
	s_nop 0
	v_add_f32_e32 v76, 1.0, v76
	v_rcp_f32_e32 v76, v76
	s_nop 0
	v_mul_f32_e32 v75, v75, v76
	v_mov_b32_e32 v76, v81
	v_mul_f32_e32 v80, v74, v75
	v_pk_mul_f32 v[74:75], v[76:77], v[170:171] op_sel_hi:[1,0]
	s_nop 0
	v_mul_f32_e32 v76, 0xbfb8aa3b, v75
	v_exp_f32_e32 v76, v76
	s_nop 0
	v_add_f32_e32 v76, 1.0, v76
	v_rcp_f32_e32 v76, v76
	s_nop 0
	v_mul_f32_e32 v75, v75, v76
	v_mul_f32_e32 v76, v74, v75
	v_mov_b32_e32 v74, v70
	v_mov_b32_e32 v75, v66
	v_pk_mul_f32 v[74:75], v[74:75], v[170:171] op_sel_hi:[1,0]
	s_nop 0
	v_mul_f32_e32 v66, 0xbfb8aa3b, v75
	v_exp_f32_e32 v66, v66
	s_nop 0
	v_add_f32_e32 v66, 1.0, v66
	v_rcp_f32_e32 v66, v66
	s_nop 0
	v_mul_f32_e32 v66, v75, v66
	v_mul_f32_e32 v70, v74, v66
	v_mov_b32_e32 v66, v71
	v_pk_mul_f32 v[66:67], v[66:67], v[170:171] op_sel_hi:[1,0]
	s_nop 0
	v_mul_f32_e32 v71, 0xbfb8aa3b, v67
	v_exp_f32_e32 v71, v71
	s_nop 0
	v_add_f32_e32 v71, 1.0, v71
	v_rcp_f32_e32 v71, v71
	s_nop 0
	v_mul_f32_e32 v67, v67, v71
	v_mul_f32_e32 v71, v66, v67
	v_mov_b32_e32 v66, v72
	v_mov_b32_e32 v67, v68
	v_pk_mul_f32 v[66:67], v[66:67], v[170:171] op_sel_hi:[1,0]
	s_nop 0
	v_mul_f32_e32 v68, 0xbfb8aa3b, v67
	v_exp_f32_e32 v68, v68
	s_nop 0
	v_add_f32_e32 v68, 1.0, v68
	v_rcp_f32_e32 v68, v68
	s_nop 0
	v_mul_f32_e32 v67, v67, v68
	v_mov_b32_e32 v68, v73
	v_mul_f32_e32 v72, v66, v67
	v_pk_mul_f32 v[66:67], v[68:69], v[170:171] op_sel_hi:[1,0]
	s_nop 0
	v_mul_f32_e32 v68, 0xbfb8aa3b, v67
; __device__ __forceinline__ unsigned cvt_pk_bf16(float lo, float hi) { unsigned r; asm volatile("v_cvt_pk_bf16_f32 %0, %1, %2" : "=v"(r) : "v"(lo), "v"(hi)); return r; }
;     __device__ __forceinline__ void operator()(const f32x4 (&acc)[2][2][4][2], const Unit& u, int wr, int wc, int fr, int fq) const {
;     ...
;         for (int ai = 0; ai < 2; ++ai)
; #pragma unroll
;             for (int m = 0; m < 4; ++m) {
;                 const int row = row0 + ai * HALF + m * 16;
;                 const float rs = rsa[ai][m];
;                 float h[8];
; #pragma unroll
;                 for (int n = 0; n < 2; ++n)
; #pragma unroll
;                     for (int e = 0; e < 4; ++e) {
;                         const float g = acc[ai][0][m][n][e] * rs, uu = acc[ai][1][m][n][e] * rs;
;                         const float sg = __builtin_amdgcn_rcpf(1.f + __builtin_amdgcn_exp2f(g * -1.4426950408889634f));
;                         h[n * 4 + e] = g * sg * uu;
;                     }
;                 u32x4 w; w.x = cvt_pk_bf16(h[0], h[1]); w.y = cvt_pk_bf16(h[2], h[3]); w.z = cvt_pk_bf16(h[4], h[5]); w.w = cvt_pk_bf16(h[6], h[7]);
;                 *(u32x4*)(H + (size_t)row * ldc + u.pn * HALF + wc * 32 + 8 * fq) = w;
	v_exp_f32_e32 v68, v68
	s_nop 0
	v_add_f32_e32 v68, 1.0, v68
	v_rcp_f32_e32 v68, v68
	s_nop 0
	v_mul_f32_e32 v67, v67, v68
	v_mul_f32_e32 v69, v66, v67
	v_cvt_pk_bf16_f32 v66, v78, v79
	v_cvt_pk_bf16_f32 v67, v80, v76
	v_cvt_pk_bf16_f32 v68, v70, v71
	v_mad_u64_u32 v[70:71], s[54:55], v162, s63, v[114:115]
	v_cvt_pk_bf16_f32 v69, v72, v69
	v_mov_b32_e32 v72, v71
	v_mad_u64_u32 v[72:73], s[54:55], v163, s63, v[72:73]
	v_mov_b32_e32 v71, v72
	v_lshl_add_u64 v[70:71], v[70:71], 0, s[52:53]
	v_lshl_add_u64 v[70:71], v[70:71], 0, s[24:25]
	v_lshl_add_u64 v[70:71], v[70:71], 0, v[174:175]
	global_store_dwordx4 v[70:71], v[66:69], off
	s_nop 1
	v_mov_b32_e32 v66, v62
	v_mov_b32_e32 v67, v58
	v_pk_mul_f32 v[66:67], v[66:67], v[166:167] op_sel_hi:[1,0]
	s_nop 0
	v_mul_f32_e32 v58, 0xbfb8aa3b, v67
	v_exp_f32_e32 v58, v58
	s_nop 0
	v_add_f32_e32 v58, 1.0, v58
	v_rcp_f32_e32 v58, v58
	s_nop 0
	v_mul_f32_e32 v58, v67, v58
	v_mul_f32_e32 v62, v66, v58
	v_mov_b32_e32 v58, v63
	v_pk_mul_f32 v[58:59], v[58:59], v[166:167] op_sel_hi:[1,0]
	s_nop 0
	v_mul_f32_e32 v63, 0xbfb8aa3b, v59
	v_exp_f32_e32 v63, v63
	s_nop 0
	v_add_f32_e32 v63, 1.0, v63
	v_rcp_f32_e32 v63, v63
	s_nop 0
	v_mul_f32_e32 v59, v59, v63
	v_mul_f32_e32 v63, v58, v59
	v_mov_b32_e32 v58, v64
	v_mov_b32_e32 v59, v60
	v_pk_mul_f32 v[58:59], v[58:59], v[166:167] op_sel_hi:[1,0]
	s_nop 0
	v_mul_f32_e32 v60, 0xbfb8aa3b, v59
	v_exp_f32_e32 v60, v60
	s_nop 0
	v_add_f32_e32 v60, 1.0, v60
	v_rcp_f32_e32 v60, v60
	s_nop 0
	v_mul_f32_e32 v59, v59, v60
	v_mov_b32_e32 v60, v65
	v_mul_f32_e32 v64, v58, v59
	v_pk_mul_f32 v[58:59], v[60:61], v[166:167] op_sel_hi:[1,0]
	s_nop 0
	v_mul_f32_e32 v60, 0xbfb8aa3b, v59
	v_exp_f32_e32 v60, v60
	s_nop 0
	v_add_f32_e32 v60, 1.0, v60
	v_rcp_f32_e32 v60, v60
	s_nop 0
	v_mul_f32_e32 v59, v59, v60
	v_mul_f32_e32 v60, v58, v59
	v_mov_b32_e32 v58, v54
	v_mov_b32_e32 v59, v50
	v_pk_mul_f32 v[58:59], v[58:59], v[166:167] op_sel_hi:[1,0]
	s_nop 0
	v_mul_f32_e32 v50, 0xbfb8aa3b, v59
	v_exp_f32_e32 v50, v50
	s_nop 0
	v_add_f32_e32 v50, 1.0, v50
	v_rcp_f32_e32 v50, v50
	s_nop 0
	v_mul_f32_e32 v50, v59, v50
	v_mul_f32_e32 v54, v58, v50
	v_mov_b32_e32 v50, v55
	v_pk_mul_f32 v[50:51], v[50:51], v[166:167] op_sel_hi:[1,0]
	s_nop 0
	v_mul_f32_e32 v55, 0xbfb8aa3b, v51
	v_exp_f32_e32 v55, v55
	s_nop 0
	v_add_f32_e32 v55, 1.0, v55
	v_rcp_f32_e32 v55, v55
	s_nop 0
	v_mul_f32_e32 v51, v51, v55
	v_mul_f32_e32 v55, v50, v51
	v_mov_b32_e32 v50, v56
	v_mov_b32_e32 v51, v52
	v_pk_mul_f32 v[50:51], v[50:51], v[166:167] op_sel_hi:[1,0]
	s_nop 0
	v_mul_f32_e32 v52, 0xbfb8aa3b, v51
	v_exp_f32_e32 v52, v52
	s_nop 0
	v_add_f32_e32 v52, 1.0, v52
	v_rcp_f32_e32 v52, v52
	s_nop 0
	v_mul_f32_e32 v51, v51, v52
	v_mov_b32_e32 v52, v57
	v_mul_f32_e32 v56, v50, v51
	v_pk_mul_f32 v[50:51], v[52:53], v[166:167] op_sel_hi:[1,0]
	s_nop 0
	v_mul_f32_e32 v52, 0xbfb8aa3b, v51
	v_exp_f32_e32 v52, v52
	s_nop 0
	v_add_f32_e32 v52, 1.0, v52
	v_rcp_f32_e32 v52, v52
	s_nop 0
	v_mul_f32_e32 v51, v51, v52
	v_mul_f32_e32 v53, v50, v51
	v_cvt_pk_bf16_f32 v50, v62, v63
	v_cvt_pk_bf16_f32 v51, v64, v60
	v_cvt_pk_bf16_f32 v52, v54, v55
	v_mad_u64_u32 v[54:55], s[54:55], v158, s63, v[114:115]
	v_cvt_pk_bf16_f32 v53, v56, v53
	v_mov_b32_e32 v56, v55
	v_mad_u64_u32 v[56:57], s[54:55], v159, s63, v[56:57]
	v_mov_b32_e32 v55, v56
	v_lshl_add_u64 v[54:55], v[54:55], 0, s[52:53]
	v_lshl_add_u64 v[54:55], v[54:55], 0, s[24:25]
	v_lshl_add_u64 v[54:55], v[54:55], 0, v[174:175]
	global_store_dwordx4 v[54:55], v[50:53], off
	s_nop 1
	v_mov_b32_e32 v50, v46
	v_mov_b32_e32 v51, v42
	v_pk_mul_f32 v[50:51], v[50:51], v[164:165] op_sel_hi:[1,0]
	s_nop 0
	v_mul_f32_e32 v42, 0xbfb8aa3b, v51
	v_exp_f32_e32 v42, v42
	s_nop 0
	v_add_f32_e32 v42, 1.0, v42
	v_rcp_f32_e32 v42, v42
	s_nop 0
	v_mul_f32_e32 v42, v51, v42
	v_mul_f32_e32 v46, v50, v42
	v_mov_b32_e32 v42, v47
	v_pk_mul_f32 v[42:43], v[42:43], v[164:165] op_sel_hi:[1,0]
	s_nop 0
	v_mul_f32_e32 v47, 0xbfb8aa3b, v43
	v_exp_f32_e32 v47, v47
	s_nop 0
	v_add_f32_e32 v47, 1.0, v47
	v_rcp_f32_e32 v47, v47
	s_nop 0
	v_mul_f32_e32 v43, v43, v47
	v_mul_f32_e32 v47, v42, v43
	v_mov_b32_e32 v42, v48
	v_mov_b32_e32 v43, v44
	v_pk_mul_f32 v[42:43], v[42:43], v[164:165] op_sel_hi:[1,0]
	s_nop 0
	v_mul_f32_e32 v44, 0xbfb8aa3b, v43
	v_exp_f32_e32 v44, v44
	s_nop 0
	v_add_f32_e32 v44, 1.0, v44
	v_rcp_f32_e32 v44, v44
	s_nop 0
	v_mul_f32_e32 v43, v43, v44
	v_mov_b32_e32 v44, v49
	v_mul_f32_e32 v48, v42, v43
	v_pk_mul_f32 v[42:43], v[44:45], v[164:165] op_sel_hi:[1,0]
	s_nop 0
	v_mul_f32_e32 v44, 0xbfb8aa3b, v43
	v_exp_f32_e32 v44, v44
	s_nop 0
	v_add_f32_e32 v44, 1.0, v44
	v_rcp_f32_e32 v44, v44
	s_nop 0
	v_mul_f32_e32 v43, v43, v44
	v_mul_f32_e32 v44, v42, v43
	v_mov_b32_e32 v42, v38
	v_mov_b32_e32 v43, v34
	v_pk_mul_f32 v[42:43], v[42:43], v[164:165] op_sel_hi:[1,0]
	s_nop 0
	v_mul_f32_e32 v34, 0xbfb8aa3b, v43
	v_exp_f32_e32 v34, v34
	s_nop 0
	v_add_f32_e32 v34, 1.0, v34
	v_rcp_f32_e32 v34, v34
	s_nop 0
	v_mul_f32_e32 v34, v43, v34
	v_mul_f32_e32 v38, v42, v34
	v_mov_b32_e32 v34, v39
	v_pk_mul_f32 v[34:35], v[34:35], v[164:165] op_sel_hi:[1,0]
	s_nop 0
	v_mul_f32_e32 v39, 0xbfb8aa3b, v35
	v_exp_f32_e32 v39, v39
	s_nop 0
	v_add_f32_e32 v39, 1.0, v39
	v_rcp_f32_e32 v39, v39
	s_nop 0
	v_mul_f32_e32 v35, v35, v39
	v_mul_f32_e32 v39, v34, v35
	v_mov_b32_e32 v34, v40
	v_mov_b32_e32 v35, v36
	v_pk_mul_f32 v[34:35], v[34:35], v[164:165] op_sel_hi:[1,0]
	s_nop 0
	v_mul_f32_e32 v36, 0xbfb8aa3b, v35
	v_exp_f32_e32 v36, v36
	s_nop 0
	v_add_f32_e32 v36, 1.0, v36
	v_rcp_f32_e32 v36, v36
	s_nop 0
	v_mul_f32_e32 v35, v35, v36
	v_mov_b32_e32 v36, v41
	v_mul_f32_e32 v40, v34, v35
	v_pk_mul_f32 v[34:35], v[36:37], v[164:165] op_sel_hi:[1,0]
; __device__ __forceinline__ unsigned cvt_pk_bf16(float lo, float hi) { unsigned r; asm volatile("v_cvt_pk_bf16_f32 %0, %1, %2" : "=v"(r) : "v"(lo), "v"(hi)); return r; }
; #define PG8_BAR __builtin_amdgcn_s_barrier()
; template <class Epi, class Sched, bool ALIGN_EPI = false, bool SP2 = false, bool F16 = false>
; __device__ __forceinline__ void gemm_phase(PG8_LAS unsigned char* lds, const Gemm g, const Sched& S, const Epi& E) {
;     ...
;         if (!has_next) break;
; #pragma unroll
;         for (int a = 0; a < 2; ++a)
; #pragma unroll
;             for (int b = 0; b < 2; ++b)
; #pragma unroll
;                 for (int m = 0; m < 4; ++m)
; #pragma unroll
;                     for (int n = 0; n < 2; ++n) acc[a][b][m][n] = (f32x4){0.f, 0.f, 0.f, 0.f};
;         cur = nxt; cA = nA; cB = nB; ++ui;
;         if constexpr (ALIGN_EPI) { if (wr == 1) PG8_BAR; }
;     __device__ __forceinline__ void operator()(const f32x4 (&acc)[2][2][4][2], const Unit& u, int wr, int wc, int fr, int fq) const {
;     ...
;         for (int ai = 0; ai < 2; ++ai)
; #pragma unroll
;             for (int m = 0; m < 4; ++m) {
;                 const int row = row0 + ai * HALF + m * 16;
;                 const float rs = rsa[ai][m];
;                 float h[8];
; #pragma unroll
;                 for (int n = 0; n < 2; ++n)
; #pragma unroll
;                     for (int e = 0; e < 4; ++e) {
;                         const float g = acc[ai][0][m][n][e] * rs, uu = acc[ai][1][m][n][e] * rs;
;                         const float sg = __builtin_amdgcn_rcpf(1.f + __builtin_amdgcn_exp2f(g * -1.4426950408889634f));
;                         h[n * 4 + e] = g * sg * uu;
;                     }
;                 u32x4 w; w.x = cvt_pk_bf16(h[0], h[1]); w.y = cvt_pk_bf16(h[2], h[3]); w.z = cvt_pk_bf16(h[4], h[5]); w.w = cvt_pk_bf16(h[6], h[7]);
;                 *(u32x4*)(H + (size_t)row * ldc + u.pn * HALF + wc * 32 + 8 * fq) = w;
;             }
	s_nop 0
	v_mul_f32_e32 v36, 0xbfb8aa3b, v35
	v_exp_f32_e32 v36, v36
	s_nop 0
	v_add_f32_e32 v36, 1.0, v36
	v_rcp_f32_e32 v36, v36
	s_nop 0
	v_mul_f32_e32 v35, v35, v36
	v_mul_f32_e32 v37, v34, v35
	v_cvt_pk_bf16_f32 v34, v46, v47
	v_cvt_pk_bf16_f32 v35, v48, v44
	v_cvt_pk_bf16_f32 v36, v38, v39
	v_mad_u64_u32 v[38:39], s[54:55], v156, s63, v[114:115]
	v_cvt_pk_bf16_f32 v37, v40, v37
	v_mov_b32_e32 v40, v39
	v_mad_u64_u32 v[40:41], s[54:55], v157, s63, v[40:41]
	v_mov_b32_e32 v39, v40
	v_lshl_add_u64 v[38:39], v[38:39], 0, s[52:53]
	v_lshl_add_u64 v[38:39], v[38:39], 0, s[24:25]
	v_lshl_add_u64 v[38:39], v[38:39], 0, v[174:175]
	global_store_dwordx4 v[38:39], v[34:37], off
	s_nop 1
	v_mov_b32_e32 v34, v30
	v_mov_b32_e32 v35, v26
	v_pk_mul_f32 v[34:35], v[34:35], v[160:161] op_sel_hi:[1,0]
	s_nop 0
	v_mul_f32_e32 v26, 0xbfb8aa3b, v35
	v_exp_f32_e32 v26, v26
	s_nop 0
	v_add_f32_e32 v26, 1.0, v26
	v_rcp_f32_e32 v26, v26
	s_nop 0
	v_mul_f32_e32 v26, v35, v26
	v_mul_f32_e32 v30, v34, v26
	v_mov_b32_e32 v26, v31
	v_pk_mul_f32 v[26:27], v[26:27], v[160:161] op_sel_hi:[1,0]
	s_nop 0
	v_mul_f32_e32 v31, 0xbfb8aa3b, v27
	v_exp_f32_e32 v31, v31
	s_nop 0
	v_add_f32_e32 v31, 1.0, v31
	v_rcp_f32_e32 v31, v31
	s_nop 0
	v_mul_f32_e32 v27, v27, v31
	v_mul_f32_e32 v31, v26, v27
	v_mov_b32_e32 v26, v32
	v_mov_b32_e32 v27, v28
	v_pk_mul_f32 v[26:27], v[26:27], v[160:161] op_sel_hi:[1,0]
	s_nop 0
	v_mul_f32_e32 v28, 0xbfb8aa3b, v27
	v_exp_f32_e32 v28, v28
	s_nop 0
	v_add_f32_e32 v28, 1.0, v28
	v_rcp_f32_e32 v28, v28
	s_nop 0
	v_mul_f32_e32 v27, v27, v28
	v_mov_b32_e32 v28, v33
	v_mul_f32_e32 v32, v26, v27
	v_pk_mul_f32 v[26:27], v[28:29], v[160:161] op_sel_hi:[1,0]
	s_nop 0
	v_mul_f32_e32 v28, 0xbfb8aa3b, v27
	v_exp_f32_e32 v28, v28
	s_nop 0
	v_add_f32_e32 v28, 1.0, v28
	v_rcp_f32_e32 v28, v28
	s_nop 0
	v_mul_f32_e32 v27, v27, v28
	v_mul_f32_e32 v28, v26, v27
	v_mov_b32_e32 v26, v22
	v_mov_b32_e32 v27, v18
	v_pk_mul_f32 v[26:27], v[26:27], v[160:161] op_sel_hi:[1,0]
	s_nop 0
	v_mul_f32_e32 v18, 0xbfb8aa3b, v27
	v_exp_f32_e32 v18, v18
	s_nop 0
	v_add_f32_e32 v18, 1.0, v18
	v_rcp_f32_e32 v18, v18
	s_nop 0
	v_mul_f32_e32 v18, v27, v18
	v_mul_f32_e32 v22, v26, v18
	v_mov_b32_e32 v18, v23
	v_pk_mul_f32 v[18:19], v[18:19], v[160:161] op_sel_hi:[1,0]
	s_nop 0
	v_mul_f32_e32 v23, 0xbfb8aa3b, v19
	v_exp_f32_e32 v23, v23
	s_nop 0
	v_add_f32_e32 v23, 1.0, v23
	v_rcp_f32_e32 v23, v23
	s_nop 0
	v_mul_f32_e32 v19, v19, v23
	v_mul_f32_e32 v23, v18, v19
	v_mov_b32_e32 v18, v24
	v_mov_b32_e32 v19, v20
	v_pk_mul_f32 v[18:19], v[18:19], v[160:161] op_sel_hi:[1,0]
	s_nop 0
	v_mul_f32_e32 v20, 0xbfb8aa3b, v19
	v_exp_f32_e32 v20, v20
	s_nop 0
	v_add_f32_e32 v20, 1.0, v20
	v_rcp_f32_e32 v20, v20
	s_nop 0
	v_mul_f32_e32 v19, v19, v20
	v_mov_b32_e32 v20, v25
	v_mul_f32_e32 v24, v18, v19
	v_pk_mul_f32 v[18:19], v[20:21], v[160:161] op_sel_hi:[1,0]
	s_nop 0
	v_mul_f32_e32 v20, 0xbfb8aa3b, v19
	v_exp_f32_e32 v20, v20
	s_nop 0
	v_add_f32_e32 v20, 1.0, v20
	v_rcp_f32_e32 v20, v20
	s_nop 0
	v_mul_f32_e32 v19, v19, v20
	v_mul_f32_e32 v21, v18, v19
	v_cvt_pk_bf16_f32 v18, v30, v31
	v_cvt_pk_bf16_f32 v19, v32, v28
	v_cvt_pk_bf16_f32 v20, v22, v23
	v_mad_u64_u32 v[22:23], s[54:55], v154, s63, v[114:115]
	v_cvt_pk_bf16_f32 v21, v24, v21
	v_mov_b32_e32 v24, v23
	v_mad_u64_u32 v[24:25], s[54:55], v155, s63, v[24:25]
	v_mov_b32_e32 v23, v24
	v_lshl_add_u64 v[22:23], v[22:23], 0, s[52:53]
	v_lshl_add_u64 v[22:23], v[22:23], 0, s[24:25]
	v_lshl_add_u64 v[22:23], v[22:23], 0, v[174:175]
	global_store_dwordx4 v[22:23], v[18:21], off
	s_nop 1
	v_mov_b32_e32 v18, v14
	v_mov_b32_e32 v19, v10
	v_pk_mul_f32 v[18:19], v[18:19], v[130:131] op_sel_hi:[1,0]
	s_nop 0
	v_mul_f32_e32 v10, 0xbfb8aa3b, v19
	v_exp_f32_e32 v10, v10
	s_nop 0
	v_add_f32_e32 v10, 1.0, v10
	v_rcp_f32_e32 v10, v10
	s_nop 0
	v_mul_f32_e32 v10, v19, v10
	v_mul_f32_e32 v14, v18, v10
	v_mov_b32_e32 v10, v15
	v_pk_mul_f32 v[10:11], v[10:11], v[130:131] op_sel_hi:[1,0]
	s_nop 0
	v_mul_f32_e32 v15, 0xbfb8aa3b, v11
	v_exp_f32_e32 v15, v15
	s_nop 0
	v_add_f32_e32 v15, 1.0, v15
	v_rcp_f32_e32 v15, v15
	s_nop 0
	v_mul_f32_e32 v11, v11, v15
	v_mul_f32_e32 v15, v10, v11
	v_mov_b32_e32 v10, v16
	v_mov_b32_e32 v11, v12
	v_pk_mul_f32 v[10:11], v[10:11], v[130:131] op_sel_hi:[1,0]
	s_nop 0
	v_mul_f32_e32 v12, 0xbfb8aa3b, v11
	v_exp_f32_e32 v12, v12
	s_nop 0
	v_add_f32_e32 v12, 1.0, v12
	v_rcp_f32_e32 v12, v12
	s_nop 0
	v_mul_f32_e32 v11, v11, v12
	v_mov_b32_e32 v12, v17
	v_mul_f32_e32 v16, v10, v11
	v_pk_mul_f32 v[10:11], v[12:13], v[130:131] op_sel_hi:[1,0]
	s_nop 0
	v_mul_f32_e32 v12, 0xbfb8aa3b, v11
	v_exp_f32_e32 v12, v12
	s_nop 0
	v_add_f32_e32 v12, 1.0, v12
	v_rcp_f32_e32 v12, v12
	s_nop 0
	v_mul_f32_e32 v11, v11, v12
	v_mul_f32_e32 v12, v10, v11
	v_mov_b32_e32 v10, v2
	v_mov_b32_e32 v11, v6
	v_pk_mul_f32 v[10:11], v[10:11], v[130:131] op_sel_hi:[1,0]
	v_mov_b32_e32 v6, v3
	v_mul_f32_e32 v2, 0xbfb8aa3b, v11
	v_exp_f32_e32 v2, v2
	s_nop 0
	v_add_f32_e32 v2, 1.0, v2
	v_rcp_f32_e32 v2, v2
	s_nop 0
	v_mul_f32_e32 v2, v11, v2
	v_mul_f32_e32 v10, v10, v2
	v_pk_mul_f32 v[2:3], v[6:7], v[130:131] op_sel_hi:[1,0]
	s_nop 0
	v_mul_f32_e32 v6, 0xbfb8aa3b, v3
	v_exp_f32_e32 v6, v6
	s_nop 0
	v_add_f32_e32 v6, 1.0, v6
	v_rcp_f32_e32 v6, v6
	s_nop 0
	v_mul_f32_e32 v3, v3, v6
	v_mul_f32_e32 v6, v2, v3
	v_mov_b32_e32 v2, v4
	v_mov_b32_e32 v3, v8
	v_pk_mul_f32 v[2:3], v[2:3], v[130:131] op_sel_hi:[1,0]
	v_mov_b32_e32 v8, v5
	v_mul_f32_e32 v4, 0xbfb8aa3b, v3
	v_exp_f32_e32 v4, v4
	s_nop 0
	v_add_f32_e32 v4, 1.0, v4
	v_rcp_f32_e32 v4, v4
	s_nop 0
	v_mul_f32_e32 v3, v3, v4
	v_mul_f32_e32 v7, v2, v3
	v_pk_mul_f32 v[2:3], v[8:9], v[130:131] op_sel_hi:[1,0]
	s_nop 0
	v_mul_f32_e32 v4, 0xbfb8aa3b, v3
	v_exp_f32_e32 v4, v4
	s_nop 0
	v_add_f32_e32 v4, 1.0, v4
	v_rcp_f32_e32 v4, v4
	s_nop 0
	v_mul_f32_e32 v3, v3, v4
	v_mul_f32_e32 v5, v2, v3
	v_cvt_pk_bf16_f32 v2, v14, v15
	v_cvt_pk_bf16_f32 v3, v16, v12
	v_cvt_pk_bf16_f32 v4, v10, v6
	v_cvt_pk_bf16_f32 v5, v7, v5
	v_mad_u64_u32 v[6:7], s[54:55], v152, s63, v[114:115]
	v_mov_b32_e32 v8, v7
	v_mad_u64_u32 v[8:9], s[54:55], v153, s63, v[8:9]
	v_mov_b32_e32 v7, v8
	v_lshl_add_u64 v[6:7], v[6:7], 0, s[52:53]
	v_lshl_add_u64 v[6:7], v[6:7], 0, s[24:25]
	v_lshl_add_u64 v[6:7], v[6:7], 0, v[174:175]
	s_mov_b64 s[52:53], -1
	global_store_dwordx4 v[6:7], v[2:5], off
	s_cbranch_vccnz .LBB0_298
	s_andn2_b64 vcc, exec, s[16:17]
	s_cbranch_vccnz .LBB0_297
	s_branch .LBB0_297

; #define PG8_BAR __builtin_amdgcn_s_barrier()
; template <class Epi, class Sched, bool ALIGN_EPI = false, bool SP2 = false, bool F16 = false>
; __device__ __forceinline__ void gemm_phase(PG8_LAS unsigned char* lds, const Gemm g, const Sched& S, const Epi& E) {
;     ...
;         if constexpr (ALIGN_EPI) { if (wr == 0) PG8_BAR; }
;         if constexpr (!Epi::AFTER_DRAIN) { E(acc, cur, wr, wc, fr, fq); S.done(cur); }
.LBB0_346:
	s_and_b64 vcc, s[38:39], s[16:17]
	s_cbranch_vccz .LBB0_348
	s_barrier

; #define PG8_BAR __builtin_amdgcn_s_barrier()
; template <class Epi, class Sched, bool ALIGN_EPI = false, bool SP2 = false, bool F16 = false>
; __device__ __forceinline__ void gemm_phase(PG8_LAS unsigned char* lds, const Gemm g, const Sched& S, const Epi& E) {
;     ...
;         if (!has_next) break;
; #pragma unroll
;         for (int a = 0; a < 2; ++a)
; #pragma unroll
;             for (int b = 0; b < 2; ++b)
; #pragma unroll
;                 for (int m = 0; m < 4; ++m)
; #pragma unroll
;                     for (int n = 0; n < 2; ++n) acc[a][b][m][n] = (f32x4){0.f, 0.f, 0.f, 0.f};
;         cur = nxt; cA = nA; cB = nB; ++ui;
;         if constexpr (ALIGN_EPI) { if (wr == 1) PG8_BAR; }
;     __device__ __forceinline__ void operator()(const f32x4 (&acc)[2][2][4][2], const Unit& u, int wr, int wc, int fr, int fq) const {
;     ...
;                     if (!(pf & 2)) *(f16x8v*)(xh + off + bj * HALF) = __builtin_convertvector(o, f16x8v);
;                     q += ((o[0] * o[0] + o[1] * o[1]) + (o[2] * o[2] + o[3] * o[3])) + ((o[4] * o[4] + o[5] * o[5]) + (o[6] * o[6] + o[7] * o[7]));
;                 }
;                 if (!(pf & 4)) { q += __shfl_xor(q, 16); q += __shfl_xor(q, 32);
;                 if (fq == 0) ssn[(size_t)row * 32 + u.pn * 4 + wc] = q; }
.LBB0_364:
	s_or_b64 exec, exec, s[54:55]
	s_and_b64 vcc, exec, s[38:39]
	s_mov_b64 s[38:39], -1
	s_cbranch_vccnz .LBB0_333
	s_andn2_b64 vcc, exec, s[14:15]
	s_cbranch_vccnz .LBB0_332
	s_branch .LBB0_332
